# attention item prologue: K0/KR0/V0/K1/KR1 tile loads issued together with counted vmcnt instead of four serialized round trips
# baseline (speedup 1.0000x reference)
; #define ATT_LOADK(rk, rr, kt_) do { if (MODE == 3 && (kt_) > 1) break; rk = *(const u32x4*)(gkn + (size_t)(kt_) * 64 * 512); rr = *(const u32x4*)(gkr + (size_t)(kt_) * 64 * 32); } while (0)
; #define ATT_LOADV(rv, kt_) do { if (MODE == 3 && (kt_) > 1) break; rv = *(const u32x4*)(gvt + (size_t)(kt_) * 64); } while (0)
; #define ATT_WRITEK(rk, rr, buf) do { LAS unsigned char* nb_ = lds + (buf) * KBUF; *(LAS u32x4*)(nb_ + skn) = rk; if (tid < 256) *(LAS u32x4*)(nb_ + skr) = rr; } while (0)
; #define ATT_WRITEV(rv, buf) do { LAS u32x2* p_ = (LAS u32x2*)(ldsv + (buf) * VBUF + svt); u32x2 lo_ = {rv[0], rv[1]}, hi_ = {rv[2], rv[3]}; p_[0] = lo_; p_[1] = hi_; } while (0)
; template <int MODE>
; __device__ __forceinline__ void attn_phase(const Args& a, bool do_ctx, LAS unsigned char* lds, const int wid_s) {
;     ...
;         const int rowbase = b * RPB;
;         const int qrow = rowbase + qt * 256 + wid * 32 + ql;
;         bf16x8 qf[6];
; #pragma unroll
;         for (int s = 0; s < 6; ++s) qf[s] = *(const bf16x8*)(Q + (size_t)qrow * 768 + h * 96 + s * 16 + hf * 8);
;         const bf16_t* gkn = KN + ((size_t)(rowbase + (tid >> 3))) * 512 + h * 64 + (tid & 7) * 8;
;         const bf16_t* gkr = KR + ((size_t)(rowbase + ((tid & 255) >> 2))) * 32 + (tid & 3) * 8;
;         const bf16_t* gvt = VT + ((size_t)((b * NH + h) * 64 + (tid >> 3))) * RPB + (tid & 7) * 8;
;         const unsigned skn = (unsigned)((tid >> 3) * KROW + (tid & 7) * 16);
;         const unsigned skr = (unsigned)(((tid & 255) >> 2) * KROW + 128 + (tid & 3) * 16);
;         const unsigned svt = (unsigned)((tid >> 3) * VROW + (tid & 7) * 16);
;     ...
;         u32x4 kK, kR, vV;
;         ATT_LOADK(kK, kR, 0); ATT_LOADV(vV, 0);
;         ATT_WRITEK(kK, kR, 0); ATT_WRITEV(vV, 0);
;         ATT_LOADK(kK, kR, 1);
;         ATT_WRITEK(kK, kR, 1);
;         __syncthreads();
;         f32x16 ot[2], sa[2], sb[2];
; #pragma unroll
;         for (int i = 0; i < 16; ++i) { ot[0][i] = 0.f; ot[1][i] = 0.f; }
;         float mrun = -3.0e38f, lsum = 0.f;
;         attn_qk<MODE>(lds, qf, sa, ql, hf);
;         __syncthreads();
.LBB0_429:
	s_mul_i32 s9, s10, 0x2100
	s_add_i32 s2, s9, s2
	v_add_u32_e32 v144, s2, v158
	v_readlane_b32 s2, v249, 54
	v_readlane_b32 s3, v249, 55
	s_and_b32 s8, s11, 7
	s_mul_i32 s76, s8, 0xc0
	v_mov_b64_e32 v[0:1], s[2:3]
	s_movk_i32 s2, 0x600
	v_mad_i64_i32 v[0:1], s[2:3], v144, s2, v[0:1]
	v_add_u32_e32 v2, s9, v159
	v_lshl_add_u64 v[0:1], v[0:1], 0, s[76:77]
	v_ashrrev_i32_e32 v3, 31, v2
	v_readlane_b32 s2, v249, 56
	v_lshl_add_u64 v[0:1], v[0:1], 0, v[200:201]
	v_lshlrev_b64 v[16:17], 10, v[2:3]
	v_readlane_b32 s3, v249, 57
	global_load_dwordx4 v[96:99], v[0:1], off offset:32
	global_load_dwordx4 v[100:103], v[0:1], off offset:64
	global_load_dwordx4 v[104:107], v[0:1], off offset:96
	global_load_dwordx4 v[108:111], v[0:1], off offset:128
	v_lshl_add_u64 v[2:3], s[2:3], 0, v[16:17]
	s_lshl_b32 s26, s8, 6
	s_lshl_b32 s2, s10, 9
	s_lshl_b32 s76, s8, 7
	s_or_b32 s2, s2, s26
	v_lshl_add_u64 v[2:3], v[2:3], 0, s[76:77]
	v_mov_b32_e32 v141, v201
	v_add_u32_e32 v8, s2, v159
	s_movk_i32 s2, 0x4200
	v_lshl_add_u64 v[4:5], v[2:3], 0, v[140:141]
	v_mad_i64_i32 v[2:3], s[2:3], v8, s2, v[138:139]
	global_load_dwordx4 v[112:115], v[0:1], off
	global_load_dwordx4 v[10:13], v[4:5], off
	global_load_dwordx4 v[116:119], v[0:1], off offset:160
	s_nop 0
	global_load_dwordx4 v[0:3], v[2:3], off
	v_or_b32_e32 v6, s9, v160
	v_ashrrev_i32_e32 v7, 31, v6
	v_lshlrev_b64 v[18:19], 6, v[6:7]
	v_lshl_add_u64 v[6:7], v[134:135], 0, v[18:19]
	global_load_dwordx4 v[120:123], v[6:7], off
	s_mov_b64 s[2:3], 0x10000
	v_lshl_add_u64 v[20:21], v[4:5], 0, s[2:3]
	s_mov_b64 s[2:3], 0x1000
	v_lshl_add_u64 v[22:23], v[6:7], 0, s[2:3]
	global_load_dwordx4 v[124:127], v[20:21], off
	global_load_dwordx4 v[128:131], v[22:23], off
	v_add_u32_e32 v141, 0xffffdc00, v251
	s_waitcnt vmcnt(5)
	ds_write_b128 v162, v[10:13]
	s_waitcnt vmcnt(3)
	ds_write2_b64 v141, v[0:1], v[2:3] offset1:2
	s_and_saveexec_b64 s[2:3], s[6:7]
	s_cbranch_execz .LBB0_431
	s_waitcnt vmcnt(2)
	ds_write_b128 v164, v[120:123] offset:128
.LBB0_431:
	s_or_b64 exec, exec, s[2:3]
	s_waitcnt vmcnt(1)
	ds_write_b128 v162, v[124:127] offset:13312
	s_and_saveexec_b64 s[2:3], s[6:7]
	s_cbranch_execz .LBB0_433
	s_waitcnt vmcnt(0)
	ds_write_b128 v164, v[128:131] offset:13440
.LBB0_433:
	s_or_b64 exec, exec, s[2:3]
	s_waitcnt vmcnt(0)
	s_movk_i32 s2, 0x4200
	v_mad_i64_i32 v[84:85], s[2:3], v8, s2, 0
	s_waitcnt lgkmcnt(0)
	s_barrier
	ds_read_b128 v[0:3], v165 offset:6656
	ds_read_b128 v[4:7], v165
	ds_read_b128 v[8:11], v165 offset:32
	ds_read_b128 v[20:23], v165 offset:6688
	ds_read_b128 v[24:27], v165 offset:64
	ds_read_b128 v[28:31], v165 offset:6720
	ds_read_b128 v[64:67], v165 offset:96
	ds_read_b128 v[68:71], v165 offset:6752
	v_ashrrev_i32_e32 v145, 31, v144
	s_waitcnt lgkmcnt(6)
	v_mfma_f32_32x32x16_bf16 v[48:63], v[4:7], v[112:115], 0
	s_mov_b32 s8, s77
	s_mov_b32 s9, s77
	s_mov_b32 s10, s77
	s_mov_b32 s11, s77
	s_mov_b32 s12, s77
	s_mov_b32 s13, s77
	s_mov_b32 s14, s77
	v_mfma_f32_32x32x16_bf16 v[32:47], v[0:3], v[112:115], 0
	s_mov_b32 s15, s77
	s_mov_b32 s16, s77
	s_mov_b32 s17, s77
	s_mov_b32 s18, s77
	s_mov_b32 s19, s77
	s_mov_b32 s20, s77
	s_mov_b32 s21, s77
	s_waitcnt lgkmcnt(5)
	v_mfma_f32_32x32x16_bf16 v[48:63], v[8:11], v[96:99], v[48:63]
	s_mov_b32 s22, s77
	s_mov_b32 s23, s77
	v_mov_b64_e32 v[0:1], s[8:9]
	v_mov_b64_e32 v[2:3], s[10:11]
	v_mov_b64_e32 v[4:5], s[12:13]
	v_mov_b64_e32 v[6:7], s[14:15]
	v_mov_b64_e32 v[8:9], s[16:17]
	s_waitcnt lgkmcnt(4)
	v_mfma_f32_32x32x16_bf16 v[32:47], v[20:23], v[96:99], v[32:47]
	v_mov_b64_e32 v[10:11], s[18:19]
	v_mov_b64_e32 v[12:13], s[20:21]
	v_mov_b64_e32 v[14:15], s[22:23]
	ds_read_b128 v[20:23], v165 offset:128
	ds_read_b128 v[72:75], v165 offset:160
	ds_read_b128 v[76:79], v165 offset:6784
	ds_read_b128 v[80:83], v165 offset:6816
	s_waitcnt lgkmcnt(7)
	v_mfma_f32_32x32x16_bf16 v[48:63], v[24:27], v[100:103], v[48:63]
	v_lshl_add_u64 v[16:17], v[136:137], 0, v[16:17]
	v_lshl_add_u64 v[146:147], v[16:17], 0, s[76:77]
	v_lshl_add_u64 v[148:149], v[132:133], 0, v[18:19]
	v_lshl_add_u64 v[150:151], v[136:137], 0, v[84:85]
	v_mov_b32_e32 v143, 0xff61b1e6
	s_mov_b32 s90, 0
	v_mov_b32_e32 v167, 0
	s_mov_b32 s12, 3
	v_readlane_b32 s18, v247, 57
	v_readlane_b32 s19, v247, 58
	s_nop 3
	s_add_u32 s80, s18, 0x31a07000
	s_addc_u32 s81, s19, 0
	s_add_u32 s82, s18, 0x33ae9000
	s_addc_u32 s83, s19, 0
	s_add_u32 s84, s18, 0x33cf7000
	s_addc_u32 s85, s19, 0
	s_waitcnt lgkmcnt(6)
	v_mfma_f32_32x32x16_bf16 v[32:47], v[28:31], v[100:103], v[32:47]
	s_waitcnt lgkmcnt(0)
	s_barrier
	v_mfma_f32_32x32x16_bf16 v[48:63], v[64:67], v[104:107], v[48:63]
	v_mfma_f32_32x32x16_bf16 v[32:47], v[68:71], v[104:107], v[32:47]
	v_mfma_f32_32x32x16_bf16 v[48:63], v[20:23], v[108:111], v[48:63]
	v_mov_b64_e32 v[30:31], v[14:15]
	v_mov_b64_e32 v[28:29], v[12:13]
	v_mov_b64_e32 v[26:27], v[10:11]
	v_mov_b64_e32 v[24:25], v[8:9]
	v_mov_b64_e32 v[22:23], v[6:7]
	v_mov_b64_e32 v[20:21], v[4:5]
	v_mov_b64_e32 v[18:19], v[2:3]
	v_mfma_f32_32x32x16_bf16 v[32:47], v[76:79], v[108:111], v[32:47]
	v_mov_b64_e32 v[16:17], v[0:1]
	v_mfma_f32_32x32x16_bf16 v[48:63], v[72:75], v[116:119], v[48:63]
	v_mfma_f32_32x32x16_bf16 v[32:47], v[80:83], v[116:119], v[32:47]
	s_branch .LBB0_435
